# qknorm+rope phase: next-row loads prefetched (2 rows in flight), DPP wave sums
# speedup vs baseline: 1.0004x; 1.0004x over previous
; __device__ __forceinline__ void qknorm_phase(const Params& p, int ja, int tid, int bid) {
;     ...
;   const float qg1 = p.in[32][(size_t)ja * 128 + lane], qg2 = p.in[32][(size_t)ja * 128 + 64 + lane];
;   const float kg1 = p.in[33][(size_t)ja * 128 + lane], kg2 = p.in[33][(size_t)ja * 128 + 64 + lane];
;   const float invf = exp2f(-(float)(lane & 31) * (13.287712379549449f / 32.f));
;   for (int row = bid * 8 + wid; row < MT; row += gridDim.x * 8) {
;     const bool lat = row < ML;
;     const int t = lat ? (row & 4095) : ((row - ML) & 255);
;     const int b = lat ? (row >> 12) : ((row - ML) >> 8);
;     const int key = lat ? CTXL + t : t;
;     float cs = 1.f, sn = 0.f;
;     if (lat) { const float pos = (float)(lane < 32 ? (t >> 6) : (t & 63)); sincosf(pos * invf, &sn, &cs); }
;     u16* qr = QKV + (size_t)row * 1536;
;     u16* kdst = KB + ((size_t)(b * 2) * NKEY + key) * 128;
;     unsigned xr1[10], xr2[10];
; #pragma unroll
;     for (int hs = 0; hs < 10; ++hs) { xr1[hs] = qr[hs * 128 + lane]; xr2[hs] = qr[hs * 128 + 64 + lane]; }
;     const u32x2 vraw = *(const u32x2*)(qr + 1280 + lane * 4);
.LBB0_179:
	s_andn2_b64 vcc, exec, s[0:1]
	s_cbranch_vccnz .LBB0_260
	v_writelane_b32 v255, s84, 55
	s_cmp_lt_i32 s64, 11
	s_mov_b64 s[0:1], -1
	v_writelane_b32 v255, s85, 56
	v_writelane_b32 v255, s86, 57
	v_writelane_b32 v255, s87, 58
	s_mov_b64 s[54:55], s[78:79]
	s_mov_b32 s31, s89
	s_cbranch_scc1 .LBB0_230
	s_cmp_gt_i32 s64, 11
	s_cbranch_scc0 .LBB0_216
	v_ashrrev_i32_e32 v0, 6, v208
	v_lshl_add_u32 v16, s62, 3, v0
	s_mov_b32 s0, 0x8800
	v_cmp_gt_i32_e32 vcc, s0, v16
	s_and_saveexec_b64 s[18:19], vcc
	s_cbranch_execz .LBB0_215
	v_and_b32_e32 v4, 63, v208
	v_lshl_or_b32 v200, s72, 7, v4
	v_readlane_b32 s4, v254, 35
	s_waitcnt lgkmcnt(0)
	v_lshlrev_b64 v[0:1], 2, v[200:201]
	v_readlane_b32 s5, v254, 36
	v_readlane_b32 s6, v254, 37
	v_readlane_b32 s7, v254, 38
	v_lshl_add_u64 v[2:3], s[4:5], 0, v[0:1]
	global_load_dword v17, v[2:3], off
	global_load_dword v18, v[2:3], off offset:256
	v_lshl_add_u64 v[0:1], s[6:7], 0, v[0:1]
	global_load_dword v19, v[0:1], off
	global_load_dword v20, v[0:1], off offset:256
	v_and_b32_e32 v2, 31, v208
	v_cvt_f32_ubyte0_e32 v0, v2
	v_mul_f32_e32 v1, 0xbed49a78, v0
	s_mov_b32 s0, 0xc2fc0000
	v_cmp_gt_f32_e32 vcc, s0, v1
	v_mov_b32_e32 v1, 0x42800000
	v_readlane_b32 s0, v253, 13
	v_cndmask_b32_e32 v1, 0, v1, vcc
	v_fmac_f32_e32 v1, 0xbed49a78, v0
	v_exp_f32_e32 v0, v1
	v_cndmask_b32_e32 v1, 0, v241, vcc
	v_lshlrev_b32_e32 v200, 1, v4
	v_readlane_b32 s1, v253, 14
	v_ldexp_f32 v21, v0, v1
	v_lshlrev_b32_e32 v6, 2, v4
	v_lshl_add_u64 v[0:1], s[0:1], 0, v[200:201]
	v_readlane_b32 s0, v253, 15
	v_lshlrev_b32_e32 v200, 3, v2
	v_readlane_b32 s1, v253, 16
	v_cmp_gt_u32_e64 s[4:5], 32, v4
	v_xor_b32_e32 v22, 0x80, v6
	v_xor_b32_e32 v23, 64, v6
	v_xor_b32_e32 v24, 32, v6
	v_xor_b32_e32 v25, 16, v6
	v_xor_b32_e32 v26, 8, v6
	v_xor_b32_e32 v27, 4, v6
	v_bfe_u32 v28, v208, 5, 1
	v_lshl_add_u64 v[2:3], s[0:1], 0, v[200:201]
	s_mov_b64 s[20:21], 0
	v_lshlrev_b32_e32 v4, 1, v4
	v_lshlrev_b32_e32 v6, 1, v6
	v_readlane_b32 s8, v254, 39
	v_readlane_b32 s9, v254, 40
	v_readlane_b32 s10, v254, 41
	v_readlane_b32 s11, v254, 42
	v_mov_b32_e32 v88, v4
	v_mov_b32_e32 v89, v201
	v_mov_b32_e32 v90, v6
	v_mov_b32_e32 v91, v201
	v_mov_b32_e32 v120, v16
	s_mov_b32 s0, 0x8000
	v_cmp_gt_i32_e32 vcc, s0, v120
	v_and_b32_e32 v9, 0xfff, v120
	v_add_u32_e32 v8, 0xffff8000, v120
	v_ashrrev_i32_e32 v7, 12, v120
	v_lshrrev_b32_e32 v8, 8, v8
	v_cndmask_b32_e32 v7, v8, v7, vcc
	v_add_u32_e32 v9, 0x100, v9
	v_mov_b64_e32 v[10:11], s[92:93]
	s_movk_i32 s0, 0xc00
	v_cndmask_b32_sdwa v200, v120, v9, vcc dst_sel:DWORD dst_unused:UNUSED_PAD src0_sel:BYTE_0 src1_sel:DWORD
	v_mad_i64_i32 v[10:11], s[0:1], v120, s0, v[10:11]
	v_lshlrev_b32_e32 v42, 1, v7
	v_lshl_add_u64 v[114:115], v[10:11], 0, v[88:89]
	v_lshl_add_u64 v[10:11], v[10:11], 0, v[90:91]
	global_load_dwordx2 v[112:113], v[10:11], off offset:2560
	global_load_ushort v92, v[114:115], off offset:0
	global_load_ushort v93, v[114:115], off offset:128
	global_load_ushort v94, v[114:115], off offset:256
	global_load_ushort v95, v[114:115], off offset:384
	global_load_ushort v96, v[114:115], off offset:512
	global_load_ushort v97, v[114:115], off offset:640
	global_load_ushort v98, v[114:115], off offset:768
	global_load_ushort v99, v[114:115], off offset:896
	global_load_ushort v100, v[114:115], off offset:1024
	global_load_ushort v101, v[114:115], off offset:1152
	global_load_ushort v102, v[114:115], off offset:1280
	global_load_ushort v103, v[114:115], off offset:1408
	global_load_ushort v104, v[114:115], off offset:1536
	global_load_ushort v105, v[114:115], off offset:1664
	global_load_ushort v106, v[114:115], off offset:1792
	global_load_ushort v107, v[114:115], off offset:1920
	global_load_ushort v108, v[114:115], off offset:2048
	global_load_ushort v109, v[114:115], off offset:2176
	global_load_ushort v110, v[114:115], off offset:2304
	global_load_ushort v111, v[114:115], off offset:2432
	s_movk_i32 s6, 0x1100
	v_mad_i64_i32 v[10:11], s[0:1], v42, s6, v[200:201]
	v_lshlrev_b64 v[10:11], 8, v[10:11]
	v_lshl_add_u64 v[116:117], v[0:1], 0, v[10:11]
	v_or_b32_e32 v9, v42, v28
	v_mad_i64_i32 v[10:11], s[0:1], v9, s6, v[200:201]
	v_lshlrev_b64 v[10:11], 8, v[10:11]
	v_lshl_add_u64 v[118:119], v[2:3], 0, v[10:11]
	s_waitcnt vmcnt(0)
	s_branch .Lqkn_enter

; __device__ __forceinline__ void qknorm_phase(const Params& p, int ja, int tid, int bid) {
;     ...
;   for (int row = bid * 8 + wid; row < MT; row += gridDim.x * 8) {
;     const bool lat = row < ML;
;     const int t = lat ? (row & 4095) : ((row - ML) & 255);
;     const int b = lat ? (row >> 12) : ((row - ML) >> 8);
;     const int key = lat ? CTXL + t : t;
;     float cs = 1.f, sn = 0.f;
;     if (lat) { const float pos = (float)(lane < 32 ? (t >> 6) : (t & 63)); sincosf(pos * invf, &sn, &cs); }
;     u16* qr = QKV + (size_t)row * 1536;
;     u16* kdst = KB + ((size_t)(b * 2) * NKEY + key) * 128;
;     unsigned xr1[10], xr2[10];
; #pragma unroll
;     for (int hs = 0; hs < 10; ++hs) { xr1[hs] = qr[hs * 128 + lane]; xr2[hs] = qr[hs * 128 + 64 + lane]; }
;     const u32x2 vraw = *(const u32x2*)(qr + 1280 + lane * 4);
.Lqkn_loop:
	s_waitcnt vmcnt(21)
.Lqkn_enter:
	v_mov_b32_e32 v48, v92
	v_mov_b32_e32 v49, v93
	v_mov_b32_e32 v50, v94
	v_mov_b32_e32 v51, v95
	v_mov_b32_e32 v52, v96
	v_mov_b32_e32 v53, v97
	v_mov_b32_e32 v54, v98
	v_mov_b32_e32 v55, v99
	v_mov_b32_e32 v56, v100
	v_mov_b32_e32 v57, v101
	v_mov_b32_e32 v58, v102
	v_mov_b32_e32 v59, v103
	v_mov_b32_e32 v60, v104
	v_mov_b32_e32 v61, v105
	v_mov_b32_e32 v62, v106
	v_mov_b32_e32 v63, v107
	v_mov_b32_e32 v64, v108
	v_mov_b32_e32 v65, v109
	v_mov_b32_e32 v66, v110
	v_mov_b32_e32 v67, v111
	v_mov_b64_e32 v[46:47], v[112:113]
	v_mov_b64_e32 v[36:37], v[114:115]
	v_mov_b64_e32 v[38:39], v[116:117]
	v_mov_b64_e32 v[40:41], v[118:119]
	v_add_u32_e32 v120, s66, v16
	s_nop 0
	v_readfirstlane_b32 s0, v120
	s_cmp_lt_i32 s0, 0x8800
	s_cbranch_scc0 .Lqkn_nopf
	s_mov_b32 s0, 0x8000
	v_cmp_gt_i32_e32 vcc, s0, v120
	v_and_b32_e32 v9, 0xfff, v120
	v_add_u32_e32 v8, 0xffff8000, v120
	v_ashrrev_i32_e32 v7, 12, v120
	v_lshrrev_b32_e32 v8, 8, v8
	v_cndmask_b32_e32 v7, v8, v7, vcc
	v_add_u32_e32 v9, 0x100, v9
	v_mov_b64_e32 v[10:11], s[92:93]
	s_movk_i32 s0, 0xc00
	v_cndmask_b32_sdwa v200, v120, v9, vcc dst_sel:DWORD dst_unused:UNUSED_PAD src0_sel:BYTE_0 src1_sel:DWORD
	v_mad_i64_i32 v[10:11], s[0:1], v120, s0, v[10:11]
	v_lshlrev_b32_e32 v42, 1, v7
	v_lshl_add_u64 v[114:115], v[10:11], 0, v[88:89]
	v_lshl_add_u64 v[10:11], v[10:11], 0, v[90:91]
	global_load_dwordx2 v[112:113], v[10:11], off offset:2560
	global_load_ushort v92, v[114:115], off offset:0
	global_load_ushort v93, v[114:115], off offset:128
	global_load_ushort v94, v[114:115], off offset:256
	global_load_ushort v95, v[114:115], off offset:384
	global_load_ushort v96, v[114:115], off offset:512
	global_load_ushort v97, v[114:115], off offset:640
	global_load_ushort v98, v[114:115], off offset:768
	global_load_ushort v99, v[114:115], off offset:896
	global_load_ushort v100, v[114:115], off offset:1024
	global_load_ushort v101, v[114:115], off offset:1152
	global_load_ushort v102, v[114:115], off offset:1280
	global_load_ushort v103, v[114:115], off offset:1408
	global_load_ushort v104, v[114:115], off offset:1536
	global_load_ushort v105, v[114:115], off offset:1664
	global_load_ushort v106, v[114:115], off offset:1792
	global_load_ushort v107, v[114:115], off offset:1920
	global_load_ushort v108, v[114:115], off offset:2048
	global_load_ushort v109, v[114:115], off offset:2176
	global_load_ushort v110, v[114:115], off offset:2304
	global_load_ushort v111, v[114:115], off offset:2432
	s_movk_i32 s6, 0x1100
	v_mad_i64_i32 v[10:11], s[0:1], v42, s6, v[200:201]
	v_lshlrev_b64 v[10:11], 8, v[10:11]
	v_lshl_add_u64 v[116:117], v[0:1], 0, v[10:11]
	v_or_b32_e32 v9, v42, v28
	v_mad_i64_i32 v[10:11], s[0:1], v9, s6, v[200:201]
	v_lshlrev_b64 v[10:11], 8, v[10:11]
	v_lshl_add_u64 v[118:119], v[2:3], 0, v[10:11]
.Lqkn_nopf:
	s_mov_b32 s0, 0x8000
	v_cmp_gt_i32_e32 vcc, s0, v16
	v_and_b32_e32 v5, 0xfff, v16
	v_mov_b32_e32 v29, 1.0
	v_mov_b32_e32 v30, 0
	s_and_saveexec_b64 s[22:23], vcc
	s_cbranch_execz .LBB0_209
	v_lshrrev_b32_e32 v7, 6, v5
	v_and_b32_e32 v8, 63, v16
	v_cndmask_b32_e64 v7, v8, v7, s[4:5]
	v_cvt_f32_ubyte0_e32 v7, v7
	v_mul_f32_e32 v7, v21, v7
	s_brev_b32 s0, 18
	v_cmp_ngt_f32_e64 s[0:1], s0, v7
	s_and_saveexec_b64 s[6:7], s[0:1]
	s_xor_b64 s[24:25], exec, s[6:7]
	s_cbranch_execz .LBB0_213
	v_lshrrev_b32_e32 v8, 23, v7
	v_add_u32_e32 v8, 0xffffff88, v8
	v_cmp_lt_u32_e64 s[0:1], 63, v8
	s_mov_b32 s10, 0xfe5163ab
	s_nop 0
	v_cndmask_b32_e64 v9, 0, v241, s[0:1]
	v_add_u32_e32 v8, v9, v8
	v_cmp_lt_u32_e64 s[6:7], 31, v8
	s_nop 1
	v_cndmask_b32_e64 v9, 0, v239, s[6:7]
	v_add_u32_e32 v8, v9, v8
	v_cmp_lt_u32_e64 s[8:9], 31, v8
	s_nop 1
	v_cndmask_b32_e64 v9, 0, v239, s[8:9]
	v_add_u32_e32 v29, v9, v8
	v_and_b32_e32 v8, 0x7fffff, v7
	v_or_b32_e32 v34, 0x800000, v8
	v_mad_u64_u32 v[8:9], s[10:11], v34, s10, 0
	v_mov_b32_e32 v200, v9
	s_mov_b32 s10, 0x3c439041
	v_mad_u64_u32 v[10:11], s[10:11], v34, s10, v[200:201]
	v_mov_b32_e32 v200, v11
	s_mov_b32 s10, 0xdb629599
	v_mad_u64_u32 v[12:13], s[10:11], v34, s10, v[200:201]
	v_mov_b32_e32 v200, v13
	s_mov_b32 s10, 0xf534ddc0
	v_mad_u64_u32 v[14:15], s[10:11], v34, s10, v[200:201]
	v_mov_b32_e32 v200, v15
	s_mov_b32 s10, 0xfc2757d1
	v_mad_u64_u32 v[30:31], s[10:11], v34, s10, v[200:201]
	v_mov_b32_e32 v200, v31
	s_mov_b32 s10, 0x4e441529
	v_mad_u64_u32 v[32:33], s[10:11], v34, s10, v[200:201]
	v_mov_b32_e32 v200, v33
	s_mov_b32 s10, 0xa2f9836e
	v_mad_u64_u32 v[34:35], s[10:11], v34, s10, v[200:201]
	v_cndmask_b32_e64 v9, v32, v14, s[0:1]
	v_cndmask_b32_e64 v11, v34, v30, s[0:1]
	v_cndmask_b32_e64 v15, v35, v32, s[0:1]
	v_cndmask_b32_e64 v13, v11, v9, s[6:7]
	v_cndmask_b32_e64 v11, v15, v11, s[6:7]
	v_cndmask_b32_e64 v15, v30, v12, s[0:1]
	v_cndmask_b32_e64 v9, v9, v15, s[6:7]
	v_cndmask_b32_e64 v10, v14, v10, s[0:1]
	v_cndmask_b32_e64 v11, v11, v13, s[8:9]
	v_cndmask_b32_e64 v13, v13, v9, s[8:9]
	v_sub_u32_e32 v30, 32, v29
	v_cndmask_b32_e64 v14, v15, v10, s[6:7]
	v_alignbit_b32 v31, v11, v13, v30
	v_cmp_eq_u32_e64 s[10:11], 0, v29
	v_cndmask_b32_e64 v9, v9, v14, s[8:9]
	v_alignbit_b32 v15, v13, v9, v30
	v_cndmask_b32_e64 v11, v31, v11, s[10:11]
	v_cndmask_b32_e64 v8, v12, v8, s[0:1]
	v_cndmask_b32_e64 v13, v15, v13, s[10:11]
	v_bfe_u32 v31, v11, 29, 1
	v_cndmask_b32_e64 v8, v10, v8, s[6:7]
	v_alignbit_b32 v15, v11, v13, 30
	v_sub_u32_e32 v32, 0, v31
	v_cndmask_b32_e64 v8, v14, v8, s[8:9]
	v_xor_b32_e32 v15, v15, v32
	v_alignbit_b32 v10, v9, v8, v30
	v_cndmask_b32_e64 v9, v10, v9, s[10:11]
	v_ffbh_u32_e32 v12, v15
	v_alignbit_b32 v10, v13, v9, 30
	v_min_u32_e32 v12, 32, v12
	v_alignbit_b32 v8, v9, v8, 30
	v_xor_b32_e32 v10, v10, v32
	v_sub_u32_e32 v13, 31, v12
	v_xor_b32_e32 v8, v8, v32
	v_alignbit_b32 v14, v15, v10, v13
	v_alignbit_b32 v8, v10, v8, v13
	v_alignbit_b32 v9, v14, v8, 9
	v_ffbh_u32_e32 v10, v9
	v_min_u32_e32 v10, 32, v10
	v_lshrrev_b32_e32 v29, 29, v11
	v_not_b32_e32 v13, v10
	v_alignbit_b32 v8, v9, v8, v13
	v_lshlrev_b32_e32 v9, 31, v29
	v_or_b32_e32 v13, 0x33000000, v9
	v_add_lshl_u32 v10, v10, v12, 23
	v_lshrrev_b32_e32 v8, 9, v8
	v_sub_u32_e32 v10, v13, v10
	v_or_b32_e32 v9, 0.5, v9
	v_lshlrev_b32_e32 v12, 23, v12
	v_or_b32_e32 v8, v10, v8
	v_lshrrev_b32_e32 v10, 9, v14
	v_sub_u32_e32 v9, v9, v12
	v_or_b32_e32 v9, v10, v9
	v_mul_f32_e32 v10, 0x3fc90fda, v9
	s_mov_b32 s0, 0x3fc90fda
	v_fma_f32 v12, v9, s0, -v10
	v_fmac_f32_e32 v12, 0x33a22168, v9
	v_fmac_f32_e32 v12, 0x3fc90fda, v8
	v_lshrrev_b32_e32 v9, 30, v11
	v_add_f32_e32 v8, v10, v12
	v_add_u32_e32 v9, v31, v9
; #define wave_sum(v) wave_sum_l((v), lane)
; __device__ __forceinline__ void qknorm_phase(const Params& p, int ja, int tid, int bid) {
;     ...
;     if (lat) { const float pos = (float)(lane < 32 ? (t >> 6) : (t & 63)); sincosf(pos * invf, &sn, &cs); }
;     u16* qr = QKV + (size_t)row * 1536;
;     u16* kdst = KB + ((size_t)(b * 2) * NKEY + key) * 128;
;     unsigned xr1[10], xr2[10];
; #pragma unroll
;     for (int hs = 0; hs < 10; ++hs) { xr1[hs] = qr[hs * 128 + lane]; xr2[hs] = qr[hs * 128 + 64 + lane]; }
;     const u32x2 vraw = *(const u32x2*)(qr + 1280 + lane * 4);
; #pragma unroll
;     for (int hs = 0; hs < 10; ++hs) {
;       const float x1 = __uint_as_float(xr1[hs] << 16), x2 = __uint_as_float(xr2[hs] << 16);
;       const float ss = wave_sum(x1 * x1 + x2 * x2);
;       const float rstd = rsqrtf(ss * (1.f / 128.f) + EPSN);
;       const float y1 = x1 * rstd * (hs < 8 ? qg1 : kg1), y2 = x2 * rstd * (hs < 8 ? qg2 : kg2);
.LBB0_213:
	s_andn2_saveexec_b64 s[0:1], s[24:25]
	s_cbranch_execz .LBB0_208
	v_mul_f32_e32 v8, 0x3f22f983, v7
	v_rndne_f32_e32 v10, v8
	v_cvt_i32_f32_e32 v9, v10
	v_fmamk_f32 v8, v10, 0xbfc90fda, v7
	v_fmac_f32_e32 v8, 0xb3a22168, v10
	v_fmac_f32_e32 v8, 0xa7c234c4, v10
	s_branch .LBB0_208
.LBB0_208:
	s_or_b64 exec, exec, s[0:1]
	v_mul_f32_e32 v10, v8, v8
	v_mov_b32_e32 v11, 0x3c0881c4
	v_fmamk_f32 v11, v10, 0xb94c1982, v11
	v_fmaak_f32 v11, v10, v11, 0xbe2aaa9d
	v_mul_f32_e32 v11, v10, v11
	v_fmac_f32_e32 v8, v8, v11
	v_mov_b32_e32 v11, 0xbab64f3b
	v_fmamk_f32 v11, v10, 0x37d75334, v11
	v_fmaak_f32 v11, v10, v11, 0x3d2aabf7
	v_fmaak_f32 v11, v10, v11, 0xbf000004
	v_fma_f32 v10, v10, v11, 1.0
	v_lshlrev_b32_e32 v11, 30, v9
	v_and_b32_e32 v9, 1, v9
	v_cmp_eq_u32_e64 s[0:1], 0, v9
	s_brev_b32 s6, 1
	s_nop 0
	v_cndmask_b32_e64 v9, v10, v8, s[0:1]
	v_xor_b32_e32 v8, 0x80000000, v8
	v_cndmask_b32_e64 v8, v8, v10, s[0:1]
	s_mov_b32 s0, 0x7f800000
	v_bitop3_b32 v9, v9, v11, s6 bitop3:0x78
	v_bitop3_b32 v8, v8, v11, s6 bitop3:0x78
	v_cmp_lg_f32_e64 s[0:1], s0, v7
	s_nop 1
	v_cndmask_b32_e64 v29, v251, v8, s[0:1]
	v_cndmask_b32_e64 v30, v251, v9, s[0:1]
.LBB0_209:
	s_or_b64 exec, exec, s[22:23]
	v_lshlrev_b32_e32 v48, 16, v48
	v_lshlrev_b32_e32 v49, 16, v49
	v_lshlrev_b32_e32 v50, 16, v50
	v_lshlrev_b32_e32 v51, 16, v51
	v_lshlrev_b32_e32 v52, 16, v52
	v_lshlrev_b32_e32 v53, 16, v53
	v_lshlrev_b32_e32 v54, 16, v54
	v_lshlrev_b32_e32 v55, 16, v55
	v_lshlrev_b32_e32 v56, 16, v56
	v_lshlrev_b32_e32 v57, 16, v57
	v_lshlrev_b32_e32 v58, 16, v58
	v_lshlrev_b32_e32 v59, 16, v59
	v_lshlrev_b32_e32 v60, 16, v60
	v_lshlrev_b32_e32 v61, 16, v61
	v_lshlrev_b32_e32 v62, 16, v62
	v_lshlrev_b32_e32 v63, 16, v63
	v_lshlrev_b32_e32 v64, 16, v64
	v_lshlrev_b32_e32 v65, 16, v65
	v_lshlrev_b32_e32 v66, 16, v66
	v_lshlrev_b32_e32 v67, 16, v67
	v_mul_f32_e32 v68, v48, v48
	v_mul_f32_e32 v69, v50, v50
	v_mul_f32_e32 v70, v52, v52
	v_mul_f32_e32 v71, v54, v54
	v_mul_f32_e32 v72, v56, v56
	v_mul_f32_e32 v73, v58, v58
	v_mul_f32_e32 v74, v60, v60
	v_mul_f32_e32 v75, v62, v62
	v_mul_f32_e32 v76, v64, v64
	v_mul_f32_e32 v77, v66, v66
	v_fmac_f32_e32 v68, v49, v49
	v_fmac_f32_e32 v69, v51, v51
	v_fmac_f32_e32 v70, v53, v53
	v_fmac_f32_e32 v71, v55, v55
	v_fmac_f32_e32 v72, v57, v57
	v_fmac_f32_e32 v73, v59, v59
	v_fmac_f32_e32 v74, v61, v61
	v_fmac_f32_e32 v75, v63, v63
	v_fmac_f32_e32 v76, v65, v65
	v_fmac_f32_e32 v77, v67, v67
	v_add_f32_dpp v68, v68, v68 quad_perm:[1,0,3,2] row_mask:0xf bank_mask:0xf
	v_add_f32_dpp v69, v69, v69 quad_perm:[1,0,3,2] row_mask:0xf bank_mask:0xf
	v_add_f32_dpp v70, v70, v70 quad_perm:[1,0,3,2] row_mask:0xf bank_mask:0xf
	v_add_f32_dpp v71, v71, v71 quad_perm:[1,0,3,2] row_mask:0xf bank_mask:0xf
	v_add_f32_dpp v72, v72, v72 quad_perm:[1,0,3,2] row_mask:0xf bank_mask:0xf
	v_add_f32_dpp v73, v73, v73 quad_perm:[1,0,3,2] row_mask:0xf bank_mask:0xf
	v_add_f32_dpp v74, v74, v74 quad_perm:[1,0,3,2] row_mask:0xf bank_mask:0xf
	v_add_f32_dpp v75, v75, v75 quad_perm:[1,0,3,2] row_mask:0xf bank_mask:0xf
	v_add_f32_dpp v76, v76, v76 quad_perm:[1,0,3,2] row_mask:0xf bank_mask:0xf
	v_add_f32_dpp v77, v77, v77 quad_perm:[1,0,3,2] row_mask:0xf bank_mask:0xf
	v_add_f32_dpp v68, v68, v68 quad_perm:[2,3,0,1] row_mask:0xf bank_mask:0xf
	v_add_f32_dpp v69, v69, v69 quad_perm:[2,3,0,1] row_mask:0xf bank_mask:0xf
	v_add_f32_dpp v70, v70, v70 quad_perm:[2,3,0,1] row_mask:0xf bank_mask:0xf
	v_add_f32_dpp v71, v71, v71 quad_perm:[2,3,0,1] row_mask:0xf bank_mask:0xf
	v_add_f32_dpp v72, v72, v72 quad_perm:[2,3,0,1] row_mask:0xf bank_mask:0xf
	v_add_f32_dpp v73, v73, v73 quad_perm:[2,3,0,1] row_mask:0xf bank_mask:0xf
	v_add_f32_dpp v74, v74, v74 quad_perm:[2,3,0,1] row_mask:0xf bank_mask:0xf
	v_add_f32_dpp v75, v75, v75 quad_perm:[2,3,0,1] row_mask:0xf bank_mask:0xf
	v_add_f32_dpp v76, v76, v76 quad_perm:[2,3,0,1] row_mask:0xf bank_mask:0xf
	v_add_f32_dpp v77, v77, v77 quad_perm:[2,3,0,1] row_mask:0xf bank_mask:0xf
	v_add_f32_dpp v68, v68, v68 row_half_mirror row_mask:0xf bank_mask:0xf
	v_add_f32_dpp v69, v69, v69 row_half_mirror row_mask:0xf bank_mask:0xf
	v_add_f32_dpp v70, v70, v70 row_half_mirror row_mask:0xf bank_mask:0xf
	v_add_f32_dpp v71, v71, v71 row_half_mirror row_mask:0xf bank_mask:0xf
	v_add_f32_dpp v72, v72, v72 row_half_mirror row_mask:0xf bank_mask:0xf
	v_add_f32_dpp v73, v73, v73 row_half_mirror row_mask:0xf bank_mask:0xf
	v_add_f32_dpp v74, v74, v74 row_half_mirror row_mask:0xf bank_mask:0xf
	v_add_f32_dpp v75, v75, v75 row_half_mirror row_mask:0xf bank_mask:0xf
	v_add_f32_dpp v76, v76, v76 row_half_mirror row_mask:0xf bank_mask:0xf
	v_add_f32_dpp v77, v77, v77 row_half_mirror row_mask:0xf bank_mask:0xf
	v_add_f32_dpp v68, v68, v68 row_mirror row_mask:0xf bank_mask:0xf
	v_add_f32_dpp v69, v69, v69 row_mirror row_mask:0xf bank_mask:0xf
	v_add_f32_dpp v70, v70, v70 row_mirror row_mask:0xf bank_mask:0xf
	v_add_f32_dpp v71, v71, v71 row_mirror row_mask:0xf bank_mask:0xf
	v_add_f32_dpp v72, v72, v72 row_mirror row_mask:0xf bank_mask:0xf
	v_add_f32_dpp v73, v73, v73 row_mirror row_mask:0xf bank_mask:0xf
	v_add_f32_dpp v74, v74, v74 row_mirror row_mask:0xf bank_mask:0xf
	v_add_f32_dpp v75, v75, v75 row_mirror row_mask:0xf bank_mask:0xf
	v_add_f32_dpp v76, v76, v76 row_mirror row_mask:0xf bank_mask:0xf
	v_add_f32_dpp v77, v77, v77 row_mirror row_mask:0xf bank_mask:0xf
	v_mov_b32_e32 v78, v68
	v_mov_b32_e32 v79, v69
	v_mov_b32_e32 v80, v70
	v_mov_b32_e32 v81, v71
	v_mov_b32_e32 v82, v72
	v_mov_b32_e32 v83, v73
	v_mov_b32_e32 v84, v74
	v_mov_b32_e32 v85, v75
	v_mov_b32_e32 v86, v76
	v_mov_b32_e32 v87, v77
	v_permlane16_swap_b32_e32 v78, v68
; __device__ __forceinline__ u16 f2bf(float x) { return (u16)(cvtpk(x, 0.f) & 0xffffu); }
; #define wave_sum(v) wave_sum_l((v), lane)
; __device__ __forceinline__ void qknorm_phase(const Params& p, int ja, int tid, int bid) {
;     ...
;     for (int hs = 0; hs < 10; ++hs) {
;       const float x1 = __uint_as_float(xr1[hs] << 16), x2 = __uint_as_float(xr2[hs] << 16);
;       const float ss = wave_sum(x1 * x1 + x2 * x2);
;       const float rstd = rsqrtf(ss * (1.f / 128.f) + EPSN);
;       const float y1 = x1 * rstd * (hs < 8 ? qg1 : kg1), y2 = x2 * rstd * (hs < 8 ? qg2 : kg2);
;       const float o1 = y1 * cs - y2 * sn, o2 = y1 * sn + y2 * cs;
;       if (hs < 8) { qr[hs * 128 + lane] = f2bf(o1); qr[hs * 128 + 64 + lane] = f2bf(o2); }
;       else { u16* kd2 = kdst + (size_t)(hs - 8) * NKEY * 128; kd2[lane] = f2bf(o1); kd2[64 + lane] = f2bf(o2); }
;     }
;     *(u32x2*)(VB + ((size_t)(b * 2 + (lane >> 5)) * NKEY + key) * 128 + (lane & 31) * 4) = vraw;
;   }
	v_permlane16_swap_b32_e32 v79, v69
	v_permlane16_swap_b32_e32 v80, v70
	v_permlane16_swap_b32_e32 v81, v71
	v_permlane16_swap_b32_e32 v82, v72
	v_permlane16_swap_b32_e32 v83, v73
	v_permlane16_swap_b32_e32 v84, v74
	v_permlane16_swap_b32_e32 v85, v75
	v_permlane16_swap_b32_e32 v86, v76
	v_permlane16_swap_b32_e32 v87, v77
	v_add_f32_e32 v68, v68, v78
	v_add_f32_e32 v69, v69, v79
	v_add_f32_e32 v70, v70, v80
	v_add_f32_e32 v71, v71, v81
	v_add_f32_e32 v72, v72, v82
	v_add_f32_e32 v73, v73, v83
	v_add_f32_e32 v74, v74, v84
	v_add_f32_e32 v75, v75, v85
	v_add_f32_e32 v76, v76, v86
	v_add_f32_e32 v77, v77, v87
	v_mov_b32_e32 v78, v68
	v_mov_b32_e32 v79, v69
	v_mov_b32_e32 v80, v70
	v_mov_b32_e32 v81, v71
	v_mov_b32_e32 v82, v72
	v_mov_b32_e32 v83, v73
	v_mov_b32_e32 v84, v74
	v_mov_b32_e32 v85, v75
	v_mov_b32_e32 v86, v76
	v_mov_b32_e32 v87, v77
	v_permlane32_swap_b32_e32 v78, v68
	v_permlane32_swap_b32_e32 v79, v69
	v_permlane32_swap_b32_e32 v80, v70
	v_permlane32_swap_b32_e32 v81, v71
	v_permlane32_swap_b32_e32 v82, v72
	v_permlane32_swap_b32_e32 v83, v73
	v_permlane32_swap_b32_e32 v84, v74
	v_permlane32_swap_b32_e32 v85, v75
	v_permlane32_swap_b32_e32 v86, v76
	v_permlane32_swap_b32_e32 v87, v77
	v_add_f32_e32 v68, v68, v78
	v_add_f32_e32 v69, v69, v79
	v_add_f32_e32 v70, v70, v80
	v_add_f32_e32 v71, v71, v81
	v_add_f32_e32 v72, v72, v82
	v_add_f32_e32 v73, v73, v83
	v_add_f32_e32 v74, v74, v84
	v_add_f32_e32 v75, v75, v85
	v_add_f32_e32 v76, v76, v86
	v_add_f32_e32 v77, v77, v87
	v_fmamk_f32 v68, v68, 0x3c000000, v202
	v_fmamk_f32 v69, v69, 0x3c000000, v202
	v_fmamk_f32 v70, v70, 0x3c000000, v202
	v_fmamk_f32 v71, v71, 0x3c000000, v202
	v_fmamk_f32 v72, v72, 0x3c000000, v202
	v_fmamk_f32 v73, v73, 0x3c000000, v202
	v_fmamk_f32 v74, v74, 0x3c000000, v202
	v_fmamk_f32 v75, v75, 0x3c000000, v202
	v_fmamk_f32 v76, v76, 0x3c000000, v202
	v_fmamk_f32 v77, v77, 0x3c000000, v202
	v_rsq_f32_e32 v68, v68
	v_rsq_f32_e32 v69, v69
	v_rsq_f32_e32 v70, v70
	v_rsq_f32_e32 v71, v71
	v_rsq_f32_e32 v72, v72
	v_rsq_f32_e32 v73, v73
	v_rsq_f32_e32 v74, v74
	v_rsq_f32_e32 v75, v75
	v_rsq_f32_e32 v76, v76
	v_rsq_f32_e32 v77, v77
	v_mul_f32_e32 v49, v68, v49
	v_mul_f32_e32 v48, v68, v48
	v_mul_f32_e32 v49, v18, v49
	v_mul_f32_e32 v48, v17, v48
	v_mul_f32_e32 v78, v29, v49
	v_mul_f32_e32 v49, v30, v49
	v_fmac_f32_e32 v78, v30, v48
	v_fma_f32 v48, v29, v48, -v49
	v_mul_f32_e32 v51, v69, v51
	v_mul_f32_e32 v50, v69, v50
	v_mul_f32_e32 v51, v18, v51
	v_mul_f32_e32 v50, v17, v50
	v_mul_f32_e32 v79, v29, v51
	v_mul_f32_e32 v51, v30, v51
	v_fmac_f32_e32 v79, v30, v50
	v_fma_f32 v50, v29, v50, -v51
	v_mul_f32_e32 v53, v70, v53
	v_mul_f32_e32 v52, v70, v52
	v_mul_f32_e32 v53, v18, v53
	v_mul_f32_e32 v52, v17, v52
	v_mul_f32_e32 v80, v29, v53
	v_mul_f32_e32 v53, v30, v53
	v_fmac_f32_e32 v80, v30, v52
	v_fma_f32 v52, v29, v52, -v53
	v_mul_f32_e32 v55, v71, v55
	v_mul_f32_e32 v54, v71, v54
	v_mul_f32_e32 v55, v18, v55
	v_mul_f32_e32 v54, v17, v54
	v_mul_f32_e32 v81, v29, v55
	v_mul_f32_e32 v55, v30, v55
	v_fmac_f32_e32 v81, v30, v54
	v_fma_f32 v54, v29, v54, -v55
	v_mul_f32_e32 v57, v72, v57
	v_mul_f32_e32 v56, v72, v56
	v_mul_f32_e32 v57, v18, v57
	v_mul_f32_e32 v56, v17, v56
	v_mul_f32_e32 v82, v29, v57
	v_mul_f32_e32 v57, v30, v57
	v_fmac_f32_e32 v82, v30, v56
	v_fma_f32 v56, v29, v56, -v57
	v_mul_f32_e32 v59, v73, v59
	v_mul_f32_e32 v58, v73, v58
	v_mul_f32_e32 v59, v18, v59
	v_mul_f32_e32 v58, v17, v58
	v_mul_f32_e32 v83, v29, v59
	v_mul_f32_e32 v59, v30, v59
	v_fmac_f32_e32 v83, v30, v58
	v_fma_f32 v58, v29, v58, -v59
	v_mul_f32_e32 v61, v74, v61
	v_mul_f32_e32 v60, v74, v60
	v_mul_f32_e32 v61, v18, v61
	v_mul_f32_e32 v60, v17, v60
	v_mul_f32_e32 v84, v29, v61
	v_mul_f32_e32 v61, v30, v61
	v_fmac_f32_e32 v84, v30, v60
	v_fma_f32 v60, v29, v60, -v61
	v_mul_f32_e32 v63, v75, v63
	v_mul_f32_e32 v62, v75, v62
	v_mul_f32_e32 v63, v18, v63
	v_mul_f32_e32 v62, v17, v62
	v_mul_f32_e32 v85, v29, v63
	v_mul_f32_e32 v63, v30, v63
	v_fmac_f32_e32 v85, v30, v62
	v_fma_f32 v62, v29, v62, -v63
	v_mul_f32_e32 v65, v76, v65
	v_mul_f32_e32 v64, v76, v64
	v_mul_f32_e32 v65, v20, v65
	v_mul_f32_e32 v64, v19, v64
	v_mul_f32_e32 v86, v29, v65
	v_mul_f32_e32 v65, v30, v65
	v_fmac_f32_e32 v86, v30, v64
	v_fma_f32 v64, v29, v64, -v65
	v_mul_f32_e32 v67, v77, v67
	v_mul_f32_e32 v66, v77, v66
	v_mul_f32_e32 v67, v20, v67
	v_mul_f32_e32 v66, v19, v66
	v_mul_f32_e32 v87, v29, v67
	v_mul_f32_e32 v67, v30, v67
	v_fmac_f32_e32 v87, v30, v66
	v_fma_f32 v66, v29, v66, -v67
	v_cvt_pk_bf16_f32 v48, v48, v201
	v_cvt_pk_bf16_f32 v78, v78, v201
	v_cvt_pk_bf16_f32 v50, v50, v201
	v_cvt_pk_bf16_f32 v79, v79, v201
	v_cvt_pk_bf16_f32 v52, v52, v201
	v_cvt_pk_bf16_f32 v80, v80, v201
	v_cvt_pk_bf16_f32 v54, v54, v201
	v_cvt_pk_bf16_f32 v81, v81, v201
	v_cvt_pk_bf16_f32 v56, v56, v201
	v_cvt_pk_bf16_f32 v82, v82, v201
	v_cvt_pk_bf16_f32 v58, v58, v201
	v_cvt_pk_bf16_f32 v83, v83, v201
	v_cvt_pk_bf16_f32 v60, v60, v201
	v_cvt_pk_bf16_f32 v84, v84, v201
	v_cvt_pk_bf16_f32 v62, v62, v201
	v_cvt_pk_bf16_f32 v85, v85, v201
	v_cvt_pk_bf16_f32 v64, v64, v201
	v_cvt_pk_bf16_f32 v86, v86, v201
	v_cvt_pk_bf16_f32 v66, v66, v201
	v_cvt_pk_bf16_f32 v87, v87, v201
	global_store_short v[36:37], v48, off offset:0
	global_store_short v[36:37], v78, off offset:128
	global_store_short v[36:37], v50, off offset:256
	global_store_short v[36:37], v79, off offset:384
	global_store_short v[36:37], v52, off offset:512
	global_store_short v[36:37], v80, off offset:640
	global_store_short v[36:37], v54, off offset:768
	global_store_short v[36:37], v81, off offset:896
	global_store_short v[36:37], v56, off offset:1024
	global_store_short v[36:37], v82, off offset:1152
	global_store_short v[36:37], v58, off offset:1280
	global_store_short v[36:37], v83, off offset:1408
	global_store_short v[36:37], v60, off offset:1536
	global_store_short v[36:37], v84, off offset:1664
	global_store_short v[36:37], v62, off offset:1792
	global_store_short v[36:37], v85, off offset:1920
	global_store_short v[38:39], v64, off
	global_store_short v[38:39], v86, off offset:128
	s_mov_b32 s0, 0x110000
	v_add_co_u32_e32 v38, vcc, s0, v38
	s_nop 1
	v_addc_co_u32_e32 v39, vcc, 0, v39, vcc
	global_store_short v[38:39], v66, off
	global_store_short v[38:39], v87, off offset:128
	global_store_dwordx2 v[40:41], v[46:47], off
	v_add_u32_e32 v16, s66, v16
	s_nop 0
	v_readfirstlane_b32 s0, v16
	s_cmp_lt_i32 s0, 0x8800
	s_cbranch_scc1 .Lqkn_loop
